# latent attention window mask: one signed compare + one select per score (no pad slots); mixer unit loop hands the 4th-round pool items to workgroups 32-79
# baseline (speedup 1.0000x reference)
.LBB0_387:
	s_add_i32 s31, s31, s46
	s_add_i32 s30, s30, s46
	s_cmpk_lt_i32 s31, 0x300
	s_cbranch_scc1 .Lmx_nr
	s_cmpk_lg_u32 s46, 0x100
	s_cbranch_scc1 .Lmx_nr
	s_sub_i32 s31, s31, 32
	s_sub_i32 s30, s30, 32
	s_cmpk_lt_i32 s31, 0x300
	s_cbranch_scc1 .LBB0_575
.Lmx_nr:
	s_cmp_lt_i32 s31, s20
	s_cbranch_scc0 .LBB0_575

.LBB0_562:
	s_andn2_b64 vcc, exec, s[16:17]
	s_cbranch_vccnz .LBB0_564
	s_nop 7
	s_cmp_eq_u32 s54, 2
	s_cbranch_scc1 .Lmka_hi
	v_sub_u32_e32 v102, 0xfffffeff, v99
	v_cmp_ge_i32_e64 s[16:17], 0, v102
	v_cmp_ge_i32_e64 s[18:19], 32, v102
	v_cmp_ge_i32_e64 s[54:55], 1, v102
	v_cndmask_b32_e64 v50, v234, v50, s[16:17]
	v_cmp_ge_i32_e64 s[16:17], 33, v102
	v_cndmask_b32_e64 v34, v234, v34, s[18:19]
	v_cmp_ge_i32_e64 s[18:19], 2, v102
	v_cndmask_b32_e64 v51, v234, v51, s[54:55]
	v_cmp_ge_i32_e64 s[54:55], 34, v102
	v_cndmask_b32_e64 v35, v234, v35, s[16:17]
	v_cmp_ge_i32_e64 s[16:17], 3, v102
	v_cndmask_b32_e64 v52, v234, v52, s[18:19]
	v_cmp_ge_i32_e64 s[18:19], 35, v102
	v_cndmask_b32_e64 v36, v234, v36, s[54:55]
	v_cmp_ge_i32_e64 s[54:55], 8, v102
	v_cndmask_b32_e64 v53, v234, v53, s[16:17]
	v_cmp_ge_i32_e64 s[16:17], 40, v102
	v_cndmask_b32_e64 v37, v234, v37, s[18:19]
	v_cmp_ge_i32_e64 s[18:19], 9, v102
	v_cndmask_b32_e64 v54, v234, v54, s[54:55]
	v_cmp_ge_i32_e64 s[54:55], 41, v102
	v_cndmask_b32_e64 v38, v234, v38, s[16:17]
	v_cmp_ge_i32_e64 s[16:17], 10, v102
	v_cndmask_b32_e64 v55, v234, v55, s[18:19]
	v_cmp_ge_i32_e64 s[18:19], 42, v102
	v_cndmask_b32_e64 v39, v234, v39, s[54:55]
	v_cmp_ge_i32_e64 s[54:55], 11, v102
	v_cndmask_b32_e64 v56, v234, v56, s[16:17]
	v_cmp_ge_i32_e64 s[16:17], 43, v102
	v_cndmask_b32_e64 v40, v234, v40, s[18:19]
	v_cmp_ge_i32_e64 s[18:19], 16, v102
	v_cndmask_b32_e64 v57, v234, v57, s[54:55]
	v_cmp_ge_i32_e64 s[54:55], 48, v102
	v_cndmask_b32_e64 v41, v234, v41, s[16:17]
	v_cmp_ge_i32_e64 s[16:17], 17, v102
	v_cndmask_b32_e64 v58, v234, v58, s[18:19]
	v_cmp_ge_i32_e64 s[18:19], 49, v102
	v_cndmask_b32_e64 v42, v234, v42, s[54:55]
	v_cmp_ge_i32_e64 s[54:55], 18, v102
	v_cndmask_b32_e64 v59, v234, v59, s[16:17]
	v_cmp_ge_i32_e64 s[16:17], 50, v102
	v_cndmask_b32_e64 v43, v234, v43, s[18:19]
	v_cmp_ge_i32_e64 s[18:19], 19, v102
	v_cndmask_b32_e64 v60, v234, v60, s[54:55]
	v_cmp_ge_i32_e64 s[54:55], 51, v102
	v_cndmask_b32_e64 v44, v234, v44, s[16:17]
	v_cmp_ge_i32_e64 s[16:17], 24, v102
	v_cndmask_b32_e64 v61, v234, v61, s[18:19]
	v_cmp_ge_i32_e64 s[18:19], 56, v102
	v_cndmask_b32_e64 v45, v234, v45, s[54:55]
	v_cmp_ge_i32_e64 s[54:55], 25, v102
	v_cndmask_b32_e64 v62, v234, v62, s[16:17]
	v_cmp_ge_i32_e64 s[16:17], 57, v102
	v_cndmask_b32_e64 v46, v234, v46, s[18:19]
	v_cmp_ge_i32_e64 s[18:19], 26, v102
	v_cndmask_b32_e64 v63, v234, v63, s[54:55]
	v_cmp_ge_i32_e64 s[54:55], 58, v102
	v_cndmask_b32_e64 v47, v234, v47, s[16:17]
	v_cmp_ge_i32_e64 s[16:17], 27, v102
	v_cndmask_b32_e64 v64, v234, v64, s[18:19]
	v_cmp_ge_i32_e64 s[18:19], 59, v102
	v_cndmask_b32_e64 v48, v234, v48, s[54:55]
	s_nop 0
	v_cndmask_b32_e64 v65, v234, v65, s[16:17]
	s_nop 0
	v_cndmask_b32_e64 v49, v234, v49, s[18:19]
	s_branch .Lmka_done
.Lmka_hi:
	v_sub_u32_e32 v102, 0xffffffff, v99
	v_cmp_le_i32_e64 s[16:17], 0, v102
	v_cmp_le_i32_e64 s[18:19], 32, v102
	v_cmp_le_i32_e64 s[54:55], 1, v102
	v_cndmask_b32_e64 v50, v234, v50, s[16:17]
	v_cmp_le_i32_e64 s[16:17], 33, v102
	v_cndmask_b32_e64 v34, v234, v34, s[18:19]
	v_cmp_le_i32_e64 s[18:19], 2, v102
	v_cndmask_b32_e64 v51, v234, v51, s[54:55]
	v_cmp_le_i32_e64 s[54:55], 34, v102
	v_cndmask_b32_e64 v35, v234, v35, s[16:17]
	v_cmp_le_i32_e64 s[16:17], 3, v102
	v_cndmask_b32_e64 v52, v234, v52, s[18:19]
	v_cmp_le_i32_e64 s[18:19], 35, v102
	v_cndmask_b32_e64 v36, v234, v36, s[54:55]
	v_cmp_le_i32_e64 s[54:55], 8, v102
	v_cndmask_b32_e64 v53, v234, v53, s[16:17]
	v_cmp_le_i32_e64 s[16:17], 40, v102
	v_cndmask_b32_e64 v37, v234, v37, s[18:19]
	v_cmp_le_i32_e64 s[18:19], 9, v102
	v_cndmask_b32_e64 v54, v234, v54, s[54:55]
	v_cmp_le_i32_e64 s[54:55], 41, v102
	v_cndmask_b32_e64 v38, v234, v38, s[16:17]
	v_cmp_le_i32_e64 s[16:17], 10, v102
	v_cndmask_b32_e64 v55, v234, v55, s[18:19]
	v_cmp_le_i32_e64 s[18:19], 42, v102
	v_cndmask_b32_e64 v39, v234, v39, s[54:55]
	v_cmp_le_i32_e64 s[54:55], 11, v102
	v_cndmask_b32_e64 v56, v234, v56, s[16:17]
	v_cmp_le_i32_e64 s[16:17], 43, v102
	v_cndmask_b32_e64 v40, v234, v40, s[18:19]
	v_cmp_le_i32_e64 s[18:19], 16, v102
	v_cndmask_b32_e64 v57, v234, v57, s[54:55]
	v_cmp_le_i32_e64 s[54:55], 48, v102
	v_cndmask_b32_e64 v41, v234, v41, s[16:17]
	v_cmp_le_i32_e64 s[16:17], 17, v102
	v_cndmask_b32_e64 v58, v234, v58, s[18:19]
	v_cmp_le_i32_e64 s[18:19], 49, v102
	v_cndmask_b32_e64 v42, v234, v42, s[54:55]
	v_cmp_le_i32_e64 s[54:55], 18, v102
	v_cndmask_b32_e64 v59, v234, v59, s[16:17]
	v_cmp_le_i32_e64 s[16:17], 50, v102
	v_cndmask_b32_e64 v43, v234, v43, s[18:19]
	v_cmp_le_i32_e64 s[18:19], 19, v102
	v_cndmask_b32_e64 v60, v234, v60, s[54:55]
	v_cmp_le_i32_e64 s[54:55], 51, v102
	v_cndmask_b32_e64 v44, v234, v44, s[16:17]
	v_cmp_le_i32_e64 s[16:17], 24, v102
	v_cndmask_b32_e64 v61, v234, v61, s[18:19]
	v_cmp_le_i32_e64 s[18:19], 56, v102
	v_cndmask_b32_e64 v45, v234, v45, s[54:55]
	v_cmp_le_i32_e64 s[54:55], 25, v102
	v_cndmask_b32_e64 v62, v234, v62, s[16:17]
	v_cmp_le_i32_e64 s[16:17], 57, v102
	v_cndmask_b32_e64 v46, v234, v46, s[18:19]
	v_cmp_le_i32_e64 s[18:19], 26, v102
	v_cndmask_b32_e64 v63, v234, v63, s[54:55]
	v_cmp_le_i32_e64 s[54:55], 58, v102
	v_cndmask_b32_e64 v47, v234, v47, s[16:17]
	v_cmp_le_i32_e64 s[16:17], 27, v102
	v_cndmask_b32_e64 v64, v234, v64, s[18:19]
	v_cmp_le_i32_e64 s[18:19], 59, v102
	v_cndmask_b32_e64 v48, v234, v48, s[54:55]
	s_nop 0
	v_cndmask_b32_e64 v65, v234, v65, s[16:17]
	s_nop 0
	v_cndmask_b32_e64 v49, v234, v49, s[18:19]
.Lmka_done:
.LBB0_564:
	s_nop 7
	v_max_f32_e32 v102, v51, v51
	v_max_f32_e32 v103, v50, v50
	v_max_f32_e32 v102, v103, v102
	v_max3_f32 v102, v102, v52, v53
	v_max3_f32 v102, v102, v54, v55
	v_max3_f32 v102, v102, v56, v57
	v_max3_f32 v102, v102, v58, v59
	v_max3_f32 v102, v102, v60, v61
	v_max3_f32 v102, v102, v62, v63
	v_max3_f32 v102, v102, v64, v65
	v_max3_f32 v102, v102, v34, v35
	v_max3_f32 v102, v102, v36, v37
	v_max3_f32 v102, v102, v38, v39
	v_max3_f32 v102, v102, v40, v41
	v_and_b32_e32 v103, 64, v226
	v_max3_f32 v102, v102, v42, v43
	v_xor_b32_e32 v104, 32, v226
	v_add_u32_e32 v105, 64, v103
	v_max3_f32 v102, v102, v44, v45
	v_cmp_lt_i32_e32 vcc, v104, v105
	v_max3_f32 v102, v102, v46, v47
	v_max3_f32 v102, v102, v48, v49
	v_cndmask_b32_e32 v103, v226, v104, vcc
	v_lshlrev_b32_e32 v110, 2, v103
	ds_bpermute_b32 v103, v110, v102
	v_add_u32_e32 v109, v109, v150
	s_andn2_b64 vcc, exec, s[14:15]
	s_waitcnt lgkmcnt(0)
	v_max3_f32 v107, v0, v102, v103
	v_sub_f32_e32 v118, v0, v107
	v_sub_f32_e32 v0, v50, v107
	v_exp_f32_e32 v119, v0
	v_sub_f32_e32 v0, v34, v107
	v_exp_f32_e32 v120, v0
	v_sub_f32_e32 v0, v51, v107
	v_sub_f32_e32 v34, v35, v107
	v_exp_f32_e32 v0, v0
	v_exp_f32_e32 v102, v34
	v_add_f32_e32 v103, v120, v119
	v_pk_add_f32 v[34:35], v[102:103], v[0:1]
	s_nop 0
	v_pk_add_f32 v[50:51], v[34:35], v[34:35] op_sel_hi:[0,1]
	v_sub_f32_e32 v34, v52, v107
	v_exp_f32_e32 v103, v34
	v_sub_f32_e32 v34, v36, v107
	v_exp_f32_e32 v121, v34
	v_sub_f32_e32 v34, v53, v107
	v_exp_f32_e32 v50, v34
	v_sub_f32_e32 v34, v37, v107
	v_exp_f32_e32 v34, v34
	v_add_f32_e32 v35, v121, v103
	v_pk_add_f32 v[36:37], v[34:35], v[50:51]
	v_sub_f32_e32 v35, v54, v107
	v_pk_add_f32 v[52:53], v[36:37], v[36:37] op_sel_hi:[0,1]
	v_exp_f32_e32 v51, v35
	v_sub_f32_e32 v35, v38, v107
	v_sub_f32_e32 v36, v55, v107
	v_exp_f32_e32 v35, v35
	v_exp_f32_e32 v52, v36
	v_sub_f32_e32 v36, v39, v107
	v_exp_f32_e32 v36, v36
	v_add_f32_e32 v37, v35, v51
	v_pk_add_f32 v[38:39], v[36:37], v[52:53]
	v_sub_f32_e32 v37, v56, v107
	v_pk_add_f32 v[54:55], v[38:39], v[38:39] op_sel_hi:[0,1]
	v_exp_f32_e32 v53, v37
	v_sub_f32_e32 v37, v40, v107
	v_sub_f32_e32 v38, v57, v107
	v_exp_f32_e32 v37, v37
	v_exp_f32_e32 v54, v38
	v_sub_f32_e32 v38, v41, v107
	v_exp_f32_e32 v112, v38
	v_add_f32_e32 v113, v37, v53
	v_cvt_pk_bf16_f32 v40, v35, v36
	v_pk_add_f32 v[38:39], v[112:113], v[54:55]
	s_nop 0
	v_pk_add_f32 v[56:57], v[38:39], v[38:39] op_sel_hi:[0,1]
	v_sub_f32_e32 v38, v58, v107
	v_exp_f32_e32 v55, v38
	v_sub_f32_e32 v38, v42, v107
	v_exp_f32_e32 v113, v38
	v_sub_f32_e32 v38, v59, v107
	v_exp_f32_e32 v56, v38
	v_sub_f32_e32 v38, v43, v107
	v_exp_f32_e32 v114, v38
	v_add_f32_e32 v115, v113, v55
	v_cvt_pk_bf16_f32 v41, v37, v112
	v_cvt_pk_bf16_f32 v42, v55, v56
	v_pk_add_f32 v[38:39], v[114:115], v[56:57]
	s_nop 0
	v_pk_add_f32 v[58:59], v[38:39], v[38:39] op_sel_hi:[0,1]
	v_sub_f32_e32 v38, v60, v107
	v_exp_f32_e32 v43, v38
	v_sub_f32_e32 v38, v44, v107
	v_exp_f32_e32 v57, v38
	v_sub_f32_e32 v38, v61, v107
	v_exp_f32_e32 v58, v38
	v_sub_f32_e32 v38, v45, v107
	v_exp_f32_e32 v116, v38
	v_add_f32_e32 v117, v57, v43
	v_cvt_pk_bf16_f32 v43, v43, v58
	v_pk_add_f32 v[38:39], v[116:117], v[58:59]
	s_nop 0
	v_pk_add_f32 v[44:45], v[38:39], v[38:39] op_sel_hi:[0,1]
	v_sub_f32_e32 v38, v62, v107
	v_exp_f32_e32 v59, v38
	v_sub_f32_e32 v38, v46, v107
	v_exp_f32_e32 v115, v38
	v_sub_f32_e32 v38, v63, v107
	v_exp_f32_e32 v44, v38
	v_sub_f32_e32 v38, v47, v107
	v_exp_f32_e32 v60, v38
	v_add_f32_e32 v61, v115, v59
	v_cvt_pk_bf16_f32 v35, v57, v116
	v_add_u32_e32 v58, 0x3000, v109
	v_pk_add_f32 v[38:39], v[60:61], v[44:45]
	v_cvt_pk_bf16_f32 v44, v59, v44
	v_pk_add_f32 v[46:47], v[38:39], v[38:39] op_sel_hi:[0,1]
	v_sub_f32_e32 v38, v64, v107
	v_exp_f32_e32 v45, v38
	v_sub_f32_e32 v38, v48, v107
	v_exp_f32_e32 v48, v38
	v_sub_f32_e32 v38, v65, v107
	v_exp_f32_e32 v46, v38
	v_sub_f32_e32 v38, v49, v107
	v_exp_f32_e32 v62, v38
	v_add_f32_e32 v63, v48, v45
	v_cvt_pk_bf16_f32 v45, v45, v46
	v_cvt_pk_bf16_f32 v49, v53, v54
	v_pk_add_f32 v[38:39], v[62:63], v[46:47]
	v_cvt_pk_bf16_f32 v46, v119, v0
	v_add_f32_e32 v106, v38, v39
	v_exp_f32_e32 v38, v118
	v_add_u32_e32 v0, 0x2000, v109
	v_cvt_pk_bf16_f32 v37, v48, v62
	v_cvt_pk_bf16_f32 v47, v103, v50
	v_cvt_pk_bf16_f32 v48, v51, v52
	ds_read2_b64 v[50:53], v0 offset0:128 offset1:130
	ds_read2_b64 v[54:57], v0 offset0:132 offset1:134
	v_pk_mul_f32 v[32:33], v[32:33], v[38:39] op_sel_hi:[1,0]
	v_pk_mul_f32 v[30:31], v[30:31], v[38:39] op_sel_hi:[1,0]
	v_pk_mul_f32 v[28:29], v[28:29], v[38:39] op_sel_hi:[1,0]
	v_pk_mul_f32 v[26:27], v[26:27], v[38:39] op_sel_hi:[1,0]
	v_pk_mul_f32 v[24:25], v[24:25], v[38:39] op_sel_hi:[1,0]
	v_pk_mul_f32 v[22:23], v[22:23], v[38:39] op_sel_hi:[1,0]
	v_pk_mul_f32 v[20:21], v[20:21], v[38:39] op_sel_hi:[1,0]
	v_pk_mul_f32 v[18:19], v[18:19], v[38:39] op_sel_hi:[1,0]
	v_pk_mul_f32 v[16:17], v[16:17], v[38:39] op_sel_hi:[1,0]
	v_pk_mul_f32 v[14:15], v[14:15], v[38:39] op_sel_hi:[1,0]
	s_waitcnt lgkmcnt(1)
	v_mfma_f32_32x32x16_bf16 v[18:33], v[50:53], v[46:49], v[18:33]
	ds_read2_b64 v[50:53], v58 offset0:192 offset1:194
	v_mul_f32_e64 v12, v12, v38
	v_mul_f32_e64 v13, v13, v38
	v_mul_f32_e64 v10, v10, v38
	v_mul_f32_e64 v11, v11, v38
	v_pk_mul_f32 v[8:9], v[8:9], v[38:39] op_sel_hi:[1,0]
	v_pk_mul_f32 v[6:7], v[6:7], v[38:39] op_sel_hi:[1,0]
	v_pk_mul_f32 v[4:5], v[4:5], v[38:39] op_sel_hi:[1,0]
	v_pk_mul_f32 v[2:3], v[2:3], v[38:39] op_sel_hi:[1,0]
	s_waitcnt lgkmcnt(1)
	v_mfma_f32_32x32x16_bf16 v[18:33], v[54:57], v[42:45], v[18:33]
	v_fmac_f32_e32 v106, v111, v38
	v_cvt_pk_bf16_f32 v38, v120, v102
	v_cvt_pk_bf16_f32 v39, v121, v34
	v_cvt_pk_bf16_f32 v34, v113, v114
	v_cvt_pk_bf16_f32 v36, v115, v60
	s_waitcnt lgkmcnt(0)
	v_mfma_f32_32x32x16_bf16 v[2:17], v[50:53], v[46:49], v[2:17]
	ds_read2_b64 v[46:49], v58 offset0:196 offset1:198
	s_waitcnt lgkmcnt(0)
	v_mfma_f32_32x32x16_bf16 v[2:17], v[46:49], v[42:45], v[2:17]
	ds_read2_b64 v[42:45], v0 offset0:136 offset1:138
	s_waitcnt lgkmcnt(0)
	v_mfma_f32_32x32x16_bf16 v[18:33], v[42:45], v[38:41], v[18:33]
	ds_read2_b64 v[42:45], v58 offset0:200 offset1:202
	s_waitcnt lgkmcnt(0)
	v_mfma_f32_32x32x16_bf16 v[2:17], v[42:45], v[38:41], v[2:17]
	ds_read2_b64 v[38:41], v0 offset0:140 offset1:142
	s_waitcnt lgkmcnt(0)
	v_mfma_f32_32x32x16_bf16 v[18:33], v[38:41], v[34:37], v[18:33]
	ds_read2_b64 v[38:41], v58 offset0:204 offset1:206
	s_waitcnt lgkmcnt(0)
	v_mfma_f32_32x32x16_bf16 v[2:17], v[38:41], v[34:37], v[2:17]
	s_cbranch_vccnz .LBB0_573
	ds_read_b128 v[34:37], v108 offset:18432
	ds_read_b128 v[112:115], v108 offset:18464
	s_cmp_ge_i32 s53, s36
	s_waitcnt lgkmcnt(1)
	v_mfma_f32_32x32x16_bf16 v[50:65], v[34:37], v[66:69], 0
	ds_read_b128 v[34:37], v108 offset:23040
	s_waitcnt lgkmcnt(1)
	v_mfma_f32_32x32x16_bf16 v[50:65], v[112:115], v[70:73], v[50:65]
	ds_read_b128 v[112:115], v108 offset:23072
	s_waitcnt lgkmcnt(1)
	v_mfma_f32_32x32x16_bf16 v[34:49], v[34:37], v[66:69], 0
	s_waitcnt lgkmcnt(0)
	v_mfma_f32_32x32x16_bf16 v[34:49], v[112:115], v[70:73], v[34:49]
	ds_read_b128 v[112:115], v108 offset:18496
	s_waitcnt lgkmcnt(0)
	v_mfma_f32_32x32x16_bf16 v[50:65], v[112:115], v[74:77], v[50:65]
	ds_read_b128 v[112:115], v108 offset:23104
	s_waitcnt lgkmcnt(0)
	v_mfma_f32_32x32x16_bf16 v[34:49], v[112:115], v[74:77], v[34:49]
	ds_read_b128 v[112:115], v108 offset:18528
	s_waitcnt lgkmcnt(0)
	v_mfma_f32_32x32x16_bf16 v[50:65], v[112:115], v[78:81], v[50:65]
	ds_read_b128 v[112:115], v108 offset:23136
	s_waitcnt lgkmcnt(0)
	v_mfma_f32_32x32x16_bf16 v[34:49], v[112:115], v[78:81], v[34:49]
	s_cbranch_scc1 .LBB0_572
	s_add_i32 s18, s44, s52
	s_add_i32 s18, s18, 1
	s_cmp_lt_i32 s18, 2
	s_cbranch_scc1 .LBB0_568
	s_cmp_eq_u32 s18, 2
	s_cselect_b64 s[14:15], -1, 0
	s_cbranch_execz .LBB0_569
	s_branch .LBB0_570

.LBB0_570:
	s_andn2_b64 vcc, exec, s[14:15]
	s_cbranch_vccnz .LBB0_572
	s_nop 7
	s_cmp_eq_u32 s18, 2
	s_cbranch_scc1 .Lmkb_hi
	v_sub_u32_e32 v0, 0xfffffebf, v99
	v_cmp_ge_i32_e64 s[14:15], 0, v0
	v_cmp_ge_i32_e64 s[18:19], 32, v0
	v_cmp_ge_i32_e64 s[54:55], 1, v0
	v_cndmask_b32_e64 v50, v234, v50, s[14:15]
	v_cmp_ge_i32_e64 s[14:15], 33, v0
	v_cndmask_b32_e64 v34, v234, v34, s[18:19]
	v_cmp_ge_i32_e64 s[18:19], 2, v0
	v_cndmask_b32_e64 v51, v234, v51, s[54:55]
	v_cmp_ge_i32_e64 s[54:55], 34, v0
	v_cndmask_b32_e64 v35, v234, v35, s[14:15]
	v_cmp_ge_i32_e64 s[14:15], 3, v0
	v_cndmask_b32_e64 v52, v234, v52, s[18:19]
	v_cmp_ge_i32_e64 s[18:19], 35, v0
	v_cndmask_b32_e64 v36, v234, v36, s[54:55]
	v_cmp_ge_i32_e64 s[54:55], 8, v0
	v_cndmask_b32_e64 v53, v234, v53, s[14:15]
	v_cmp_ge_i32_e64 s[14:15], 40, v0
	v_cndmask_b32_e64 v37, v234, v37, s[18:19]
	v_cmp_ge_i32_e64 s[18:19], 9, v0
	v_cndmask_b32_e64 v54, v234, v54, s[54:55]
	v_cmp_ge_i32_e64 s[54:55], 41, v0
	v_cndmask_b32_e64 v38, v234, v38, s[14:15]
	v_cmp_ge_i32_e64 s[14:15], 10, v0
	v_cndmask_b32_e64 v55, v234, v55, s[18:19]
	v_cmp_ge_i32_e64 s[18:19], 42, v0
	v_cndmask_b32_e64 v39, v234, v39, s[54:55]
	v_cmp_ge_i32_e64 s[54:55], 11, v0
	v_cndmask_b32_e64 v56, v234, v56, s[14:15]
	v_cmp_ge_i32_e64 s[14:15], 43, v0
	v_cndmask_b32_e64 v40, v234, v40, s[18:19]
	v_cmp_ge_i32_e64 s[18:19], 16, v0
	v_cndmask_b32_e64 v57, v234, v57, s[54:55]
	v_cmp_ge_i32_e64 s[54:55], 48, v0
	v_cndmask_b32_e64 v41, v234, v41, s[14:15]
	v_cmp_ge_i32_e64 s[14:15], 17, v0
	v_cndmask_b32_e64 v58, v234, v58, s[18:19]
	v_cmp_ge_i32_e64 s[18:19], 49, v0
	v_cndmask_b32_e64 v42, v234, v42, s[54:55]
	v_cmp_ge_i32_e64 s[54:55], 18, v0
	v_cndmask_b32_e64 v59, v234, v59, s[14:15]
	v_cmp_ge_i32_e64 s[14:15], 50, v0
	v_cndmask_b32_e64 v43, v234, v43, s[18:19]
	v_cmp_ge_i32_e64 s[18:19], 19, v0
	v_cndmask_b32_e64 v60, v234, v60, s[54:55]
	v_cmp_ge_i32_e64 s[54:55], 51, v0
	v_cndmask_b32_e64 v44, v234, v44, s[14:15]
	v_cmp_ge_i32_e64 s[14:15], 24, v0
	v_cndmask_b32_e64 v61, v234, v61, s[18:19]
	v_cmp_ge_i32_e64 s[18:19], 56, v0
	v_cndmask_b32_e64 v45, v234, v45, s[54:55]
	v_cmp_ge_i32_e64 s[54:55], 25, v0
	v_cndmask_b32_e64 v62, v234, v62, s[14:15]
	v_cmp_ge_i32_e64 s[14:15], 57, v0
	v_cndmask_b32_e64 v46, v234, v46, s[18:19]
	v_cmp_ge_i32_e64 s[18:19], 26, v0
	v_cndmask_b32_e64 v63, v234, v63, s[54:55]
	v_cmp_ge_i32_e64 s[54:55], 58, v0
	v_cndmask_b32_e64 v47, v234, v47, s[14:15]
	v_cmp_ge_i32_e64 s[14:15], 27, v0
	v_cndmask_b32_e64 v64, v234, v64, s[18:19]
	v_cmp_ge_i32_e64 s[18:19], 59, v0
	v_cndmask_b32_e64 v48, v234, v48, s[54:55]
	s_nop 0
	v_cndmask_b32_e64 v65, v234, v65, s[14:15]
	s_nop 0
	v_cndmask_b32_e64 v49, v234, v49, s[18:19]
	s_branch .Lmkb_done
.Lmkb_hi:
	v_sub_u32_e32 v0, 0xffffffbf, v99
	v_cmp_le_i32_e64 s[14:15], 0, v0
	v_cmp_le_i32_e64 s[18:19], 32, v0
	v_cmp_le_i32_e64 s[54:55], 1, v0
	v_cndmask_b32_e64 v50, v234, v50, s[14:15]
	v_cmp_le_i32_e64 s[14:15], 33, v0
	v_cndmask_b32_e64 v34, v234, v34, s[18:19]
	v_cmp_le_i32_e64 s[18:19], 2, v0
	v_cndmask_b32_e64 v51, v234, v51, s[54:55]
	v_cmp_le_i32_e64 s[54:55], 34, v0
	v_cndmask_b32_e64 v35, v234, v35, s[14:15]
	v_cmp_le_i32_e64 s[14:15], 3, v0
	v_cndmask_b32_e64 v52, v234, v52, s[18:19]
	v_cmp_le_i32_e64 s[18:19], 35, v0
	v_cndmask_b32_e64 v36, v234, v36, s[54:55]
	v_cmp_le_i32_e64 s[54:55], 8, v0
	v_cndmask_b32_e64 v53, v234, v53, s[14:15]
	v_cmp_le_i32_e64 s[14:15], 40, v0
	v_cndmask_b32_e64 v37, v234, v37, s[18:19]
	v_cmp_le_i32_e64 s[18:19], 9, v0
	v_cndmask_b32_e64 v54, v234, v54, s[54:55]
	v_cmp_le_i32_e64 s[54:55], 41, v0
	v_cndmask_b32_e64 v38, v234, v38, s[14:15]
	v_cmp_le_i32_e64 s[14:15], 10, v0
	v_cndmask_b32_e64 v55, v234, v55, s[18:19]
	v_cmp_le_i32_e64 s[18:19], 42, v0
	v_cndmask_b32_e64 v39, v234, v39, s[54:55]
	v_cmp_le_i32_e64 s[54:55], 11, v0
	v_cndmask_b32_e64 v56, v234, v56, s[14:15]
	v_cmp_le_i32_e64 s[14:15], 43, v0
	v_cndmask_b32_e64 v40, v234, v40, s[18:19]
	v_cmp_le_i32_e64 s[18:19], 16, v0
	v_cndmask_b32_e64 v57, v234, v57, s[54:55]
	v_cmp_le_i32_e64 s[54:55], 48, v0
	v_cndmask_b32_e64 v41, v234, v41, s[14:15]
	v_cmp_le_i32_e64 s[14:15], 17, v0
	v_cndmask_b32_e64 v58, v234, v58, s[18:19]
	v_cmp_le_i32_e64 s[18:19], 49, v0
	v_cndmask_b32_e64 v42, v234, v42, s[54:55]
	v_cmp_le_i32_e64 s[54:55], 18, v0
	v_cndmask_b32_e64 v59, v234, v59, s[14:15]
	v_cmp_le_i32_e64 s[14:15], 50, v0
	v_cndmask_b32_e64 v43, v234, v43, s[18:19]
	v_cmp_le_i32_e64 s[18:19], 19, v0
	v_cndmask_b32_e64 v60, v234, v60, s[54:55]
	v_cmp_le_i32_e64 s[54:55], 51, v0
	v_cndmask_b32_e64 v44, v234, v44, s[14:15]
	v_cmp_le_i32_e64 s[14:15], 24, v0
	v_cndmask_b32_e64 v61, v234, v61, s[18:19]
	v_cmp_le_i32_e64 s[18:19], 56, v0
	v_cndmask_b32_e64 v45, v234, v45, s[54:55]
	v_cmp_le_i32_e64 s[54:55], 25, v0
	v_cndmask_b32_e64 v62, v234, v62, s[14:15]
	v_cmp_le_i32_e64 s[14:15], 57, v0
	v_cndmask_b32_e64 v46, v234, v46, s[18:19]
	v_cmp_le_i32_e64 s[18:19], 26, v0
	v_cndmask_b32_e64 v63, v234, v63, s[54:55]
	v_cmp_le_i32_e64 s[54:55], 58, v0
	v_cndmask_b32_e64 v47, v234, v47, s[14:15]
	v_cmp_le_i32_e64 s[14:15], 27, v0
	v_cndmask_b32_e64 v64, v234, v64, s[18:19]
	v_cmp_le_i32_e64 s[18:19], 59, v0
	v_cndmask_b32_e64 v48, v234, v48, s[54:55]
	s_nop 0
	v_cndmask_b32_e64 v65, v234, v65, s[14:15]
	s_nop 0
	v_cndmask_b32_e64 v49, v234, v49, s[18:19]
.Lmkb_done:
.LBB0_572:
	s_nop 7
	v_max_f32_e32 v0, v51, v51
	v_max_f32_e32 v102, v50, v50
	v_max_f32_e32 v0, v102, v0
	v_max3_f32 v0, v0, v52, v53
	v_max3_f32 v0, v0, v54, v55
	v_max3_f32 v0, v0, v56, v57
	v_max3_f32 v0, v0, v58, v59
	v_max3_f32 v0, v0, v60, v61
	v_max3_f32 v0, v0, v62, v63
	v_max3_f32 v0, v0, v64, v65
	v_max3_f32 v0, v0, v34, v35
	v_max3_f32 v0, v0, v36, v37
	v_max3_f32 v0, v0, v38, v39
	v_max3_f32 v0, v0, v40, v41
	v_max3_f32 v0, v0, v42, v43
	v_max3_f32 v0, v0, v44, v45
	v_max3_f32 v0, v0, v46, v47
	v_max3_f32 v0, v0, v48, v49
	ds_bpermute_b32 v102, v110, v0
	s_waitcnt lgkmcnt(0)
	v_max3_f32 v108, v107, v0, v102
	v_sub_f32_e32 v0, v50, v108
	v_exp_f32_e32 v118, v0
	v_sub_f32_e32 v0, v34, v108
	v_exp_f32_e32 v119, v0
	v_sub_f32_e32 v0, v51, v108
	v_sub_f32_e32 v34, v35, v108
	v_exp_f32_e32 v0, v0
	v_exp_f32_e32 v102, v34
	v_add_f32_e32 v103, v119, v118
	v_sub_f32_e32 v107, v107, v108
	v_pk_add_f32 v[34:35], v[102:103], v[0:1]
	s_nop 0
	v_pk_add_f32 v[50:51], v[34:35], v[34:35] op_sel_hi:[0,1]
	v_sub_f32_e32 v34, v52, v108
	v_exp_f32_e32 v103, v34
	v_sub_f32_e32 v34, v36, v108
	v_exp_f32_e32 v120, v34
	v_sub_f32_e32 v34, v53, v108
	v_exp_f32_e32 v50, v34
	v_sub_f32_e32 v34, v37, v108
	v_exp_f32_e32 v34, v34
	v_add_f32_e32 v35, v120, v103
	v_pk_add_f32 v[36:37], v[34:35], v[50:51]
	v_sub_f32_e32 v35, v54, v108
	v_pk_add_f32 v[52:53], v[36:37], v[36:37] op_sel_hi:[0,1]
	v_exp_f32_e32 v51, v35
	v_sub_f32_e32 v35, v38, v108
	v_sub_f32_e32 v36, v55, v108
	v_exp_f32_e32 v35, v35
	v_exp_f32_e32 v52, v36
	v_sub_f32_e32 v36, v39, v108
	v_exp_f32_e32 v36, v36
	v_add_f32_e32 v37, v35, v51
	v_pk_add_f32 v[38:39], v[36:37], v[52:53]
	v_sub_f32_e32 v37, v56, v108
	v_pk_add_f32 v[54:55], v[38:39], v[38:39] op_sel_hi:[0,1]
	v_exp_f32_e32 v53, v37
	v_sub_f32_e32 v37, v40, v108
	v_sub_f32_e32 v38, v57, v108
	v_exp_f32_e32 v37, v37
	v_exp_f32_e32 v54, v38
	v_sub_f32_e32 v38, v41, v108
	v_exp_f32_e32 v110, v38
	v_add_f32_e32 v111, v37, v53
	v_cvt_pk_bf16_f32 v40, v35, v36
	v_pk_add_f32 v[38:39], v[110:111], v[54:55]
	s_nop 0
	v_pk_add_f32 v[56:57], v[38:39], v[38:39] op_sel_hi:[0,1]
	v_sub_f32_e32 v38, v58, v108
	v_exp_f32_e32 v55, v38
	v_sub_f32_e32 v38, v42, v108
	v_exp_f32_e32 v111, v38
	v_sub_f32_e32 v38, v59, v108
	v_exp_f32_e32 v56, v38
	v_sub_f32_e32 v38, v43, v108
	v_exp_f32_e32 v112, v38
	v_add_f32_e32 v113, v111, v55
	v_cvt_pk_bf16_f32 v42, v55, v56
	v_cvt_pk_bf16_f32 v41, v37, v110
	v_pk_add_f32 v[38:39], v[112:113], v[56:57]
	s_nop 0
	v_pk_add_f32 v[58:59], v[38:39], v[38:39] op_sel_hi:[0,1]
	v_sub_f32_e32 v38, v60, v108
	v_exp_f32_e32 v43, v38
	v_sub_f32_e32 v38, v44, v108
	v_exp_f32_e32 v57, v38
	v_sub_f32_e32 v38, v61, v108
	v_exp_f32_e32 v58, v38
	v_sub_f32_e32 v38, v45, v108
	v_exp_f32_e32 v114, v38
	v_add_f32_e32 v115, v57, v43
	v_cvt_pk_bf16_f32 v43, v43, v58
	v_pk_add_f32 v[38:39], v[114:115], v[58:59]
	s_nop 0
	v_pk_add_f32 v[44:45], v[38:39], v[38:39] op_sel_hi:[0,1]
	v_sub_f32_e32 v38, v62, v108
	v_exp_f32_e32 v59, v38
	v_sub_f32_e32 v38, v46, v108
	v_exp_f32_e32 v113, v38
	v_sub_f32_e32 v38, v63, v108
	v_exp_f32_e32 v44, v38
	v_sub_f32_e32 v38, v47, v108
	v_exp_f32_e32 v60, v38
	v_add_f32_e32 v61, v113, v59
	v_cvt_pk_bf16_f32 v35, v57, v114
	v_pk_add_f32 v[38:39], v[60:61], v[44:45]
	s_nop 0
	v_pk_add_f32 v[62:63], v[38:39], v[38:39] op_sel_hi:[0,1]
	v_sub_f32_e32 v38, v64, v108
	v_exp_f32_e32 v45, v38
	v_sub_f32_e32 v38, v48, v108
	v_exp_f32_e32 v47, v38
	v_sub_f32_e32 v38, v65, v108
	v_exp_f32_e32 v62, v38
	v_sub_f32_e32 v38, v49, v108
	v_exp_f32_e32 v116, v38
	v_add_f32_e32 v117, v47, v45
	v_cvt_pk_bf16_f32 v48, v118, v0
	v_add_u32_e32 v0, 0x6800, v109
	v_pk_add_f32 v[38:39], v[116:117], v[62:63]
	v_cvt_pk_bf16_f32 v44, v59, v44
	v_add_f32_e32 v46, v38, v39
	v_exp_f32_e32 v38, v107
	v_cvt_pk_bf16_f32 v49, v103, v50
	v_cvt_pk_bf16_f32 v50, v51, v52
	v_cvt_pk_bf16_f32 v51, v53, v54
	ds_read2_b64 v[52:55], v0 offset0:128 offset1:130
	ds_read2_b64 v[56:59], v0 offset0:132 offset1:134
	v_pk_mul_f32 v[32:33], v[32:33], v[38:39] op_sel_hi:[1,0]
	v_pk_mul_f32 v[30:31], v[30:31], v[38:39] op_sel_hi:[1,0]
	v_pk_mul_f32 v[28:29], v[28:29], v[38:39] op_sel_hi:[1,0]
	v_pk_mul_f32 v[26:27], v[26:27], v[38:39] op_sel_hi:[1,0]
	v_pk_mul_f32 v[24:25], v[24:25], v[38:39] op_sel_hi:[1,0]
	v_pk_mul_f32 v[22:23], v[22:23], v[38:39] op_sel_hi:[1,0]
	v_pk_mul_f32 v[20:21], v[20:21], v[38:39] op_sel_hi:[1,0]
	v_pk_mul_f32 v[18:19], v[18:19], v[38:39] op_sel_hi:[1,0]
	v_cvt_pk_bf16_f32 v37, v47, v116
	v_add_u32_e32 v47, 0x7800, v109
	s_waitcnt lgkmcnt(1)
	v_mfma_f32_32x32x16_bf16 v[18:33], v[52:55], v[48:51], v[18:33]
	ds_read2_b64 v[52:55], v47 offset0:192 offset1:194
	v_mul_f32_e64 v16, v16, v38
	v_mul_f32_e64 v17, v17, v38
	v_mul_f32_e64 v14, v14, v38
	v_mul_f32_e64 v15, v15, v38
	v_pk_mul_f32 v[12:13], v[12:13], v[38:39] op_sel_hi:[1,0]
	v_pk_mul_f32 v[10:11], v[10:11], v[38:39] op_sel_hi:[1,0]
	v_pk_mul_f32 v[8:9], v[8:9], v[38:39] op_sel_hi:[1,0]
	v_pk_mul_f32 v[6:7], v[6:7], v[38:39] op_sel_hi:[1,0]
	v_pk_mul_f32 v[4:5], v[4:5], v[38:39] op_sel_hi:[1,0]
	v_pk_mul_f32 v[2:3], v[2:3], v[38:39] op_sel_hi:[1,0]
	v_cvt_pk_bf16_f32 v45, v45, v62
	v_fmac_f32_e32 v46, v106, v38
	s_waitcnt lgkmcnt(0)
	v_mfma_f32_32x32x16_bf16 v[2:17], v[52:55], v[48:51], v[2:17]
	ds_read2_b64 v[48:51], v47 offset0:196 offset1:198
	v_cvt_pk_bf16_f32 v38, v119, v102
	v_cvt_pk_bf16_f32 v39, v120, v34
	v_cvt_pk_bf16_f32 v34, v111, v112
	v_cvt_pk_bf16_f32 v36, v113, v60
	v_mov_b32_e32 v107, v108
	v_mov_b32_e32 v106, v46
	v_mfma_f32_32x32x16_bf16 v[18:33], v[56:59], v[42:45], v[18:33]
	s_waitcnt lgkmcnt(0)
	v_mfma_f32_32x32x16_bf16 v[2:17], v[48:51], v[42:45], v[2:17]
	ds_read2_b64 v[42:45], v0 offset0:136 offset1:138
	s_waitcnt lgkmcnt(0)
	v_mfma_f32_32x32x16_bf16 v[18:33], v[42:45], v[38:41], v[18:33]
	ds_read2_b64 v[42:45], v47 offset0:200 offset1:202
	s_waitcnt lgkmcnt(0)
	v_mfma_f32_32x32x16_bf16 v[2:17], v[42:45], v[38:41], v[2:17]
	ds_read2_b64 v[38:41], v0 offset0:140 offset1:142
	s_waitcnt lgkmcnt(0)
	v_mfma_f32_32x32x16_bf16 v[18:33], v[38:41], v[34:37], v[18:33]
	ds_read2_b64 v[38:41], v47 offset0:204 offset1:206
	s_waitcnt lgkmcnt(0)
	v_mfma_f32_32x32x16_bf16 v[2:17], v[38:41], v[34:37], v[2:17]
